# scan consumer: packed v reads (one b128 per 4 steps)
# speedup vs baseline: 1.0042x; 1.0042x over previous
.LBB0_158:
	s_or_b64 exec, exec, s[2:3]
	s_mul_i32 s0, s73, 0x5100
	v_add_u32_e32 v1, s0, v87
	v_lshl_add_u32 v0, v125, 2, v1
	v_lshl_add_u32 v18, v78, 6, v1
	ds_read_b128 v[150:153], v0 offset:9216
	ds_read_b128 v[154:157], v0 offset:9472
	ds_read_b128 v[158:161], v0 offset:9728
	ds_read_b128 v[162:165], v0 offset:9984
	ds_read_b128 v[166:169], v0 offset:10240
	ds_read_b128 v[46:49], v18 offset:29696
	ds_read_b128 v[172:175], v0 offset:10496
	ds_read_b128 v[176:179], v0 offset:10752
	ds_read_b128 v[180:183], v0 offset:11008
	ds_read_b128 v[184:187], v0 offset:11264
	ds_read_b128 v[188:191], v0 offset:11520
	s_add_i32 s73, s73, 1
	s_cmp_eq_u32 s73, 3
	s_cselect_b32 s73, 0, s73
	s_addc_u32 s1, s1, 0
	v_lshl_add_u32 v22, s73, 2, v123
	v_add_u32_e32 v23, s1, v130
.Lc3_steps:
	s_waitcnt lgkmcnt(5)
	v_pk_mul_f32 v[8:9], v[6:7], v[160:161]
	v_pk_fma_f32 v[8:9], v[4:5], v[158:159], v[8:9]
	v_add_f32_e32 v20, v8, v9
	v_pk_mul_f32 v[12:13], v[154:155], v[46:47] op_sel_hi:[1,0]
	v_pk_mul_f32 v[14:15], v[156:157], v[46:47] op_sel_hi:[1,0]
	v_add_f32_dpp v20, v20, v20 quad_perm:[1,0,3,2] row_mask:0xf bank_mask:0xf bound_ctrl:1
	v_pk_fma_f32 v[12:13], v[4:5], v[150:151], v[12:13]
	v_pk_fma_f32 v[14:15], v[6:7], v[152:153], v[14:15]
	v_add_f32_dpp v20, v20, v20 quad_perm:[2,3,0,1] row_mask:0xf bank_mask:0xf bound_ctrl:1
	ds_read_b128 v[210:213], v0 offset:11776
	ds_read_b128 v[214:217], v0 offset:12032
	v_add_f32_dpp v20, v20, v20 row_half_mirror row_mask:0xf bank_mask:0xf bound_ctrl:1
	ds_read_b128 v[218:221], v0 offset:12288
	ds_read_b128 v[222:225], v0 offset:12544
	v_add_f32_dpp v20, v20, v20 row_mirror row_mask:0xf bank_mask:0xf bound_ctrl:1
	ds_read_b128 v[226:229], v0 offset:12800
	v_pk_fma_f32 v[4:5], v[162:163], v[20:21], v[12:13] op_sel_hi:[1,0,1]
	v_pk_fma_f32 v[6:7], v[164:165], v[20:21], v[14:15] op_sel_hi:[1,0,1]
	s_waitcnt lgkmcnt(5)
	v_pk_mul_f32 v[8:9], v[6:7], v[182:183]
	v_pk_fma_f32 v[8:9], v[4:5], v[180:181], v[8:9]
	v_pk_mul_f32 v[10:11], v[6:7], v[168:169]
	v_add_f32_e32 v20, v8, v9
	v_pk_fma_f32 v[10:11], v[4:5], v[166:167], v[10:11]
	v_pk_mul_f32 v[12:13], v[176:177], v[46:47] op_sel:[0,1] op_sel_hi:[1,1]
	v_add_f32_dpp v20, v20, v20 quad_perm:[1,0,3,2] row_mask:0xf bank_mask:0xf bound_ctrl:1
	v_add_f32_e32 v30, v10, v11
	v_pk_mul_f32 v[14:15], v[178:179], v[46:47] op_sel:[0,1] op_sel_hi:[1,1]
	v_add_f32_dpp v20, v20, v20 quad_perm:[2,3,0,1] row_mask:0xf bank_mask:0xf bound_ctrl:1
	ds_read_b128 v[150:153], v0 offset:13056
	ds_read_b128 v[154:157], v0 offset:13312
	v_add_f32_dpp v20, v20, v20 row_half_mirror row_mask:0xf bank_mask:0xf bound_ctrl:1
	ds_read_b128 v[158:161], v0 offset:13568
	ds_read_b128 v[162:165], v0 offset:13824
	v_add_f32_dpp v20, v20, v20 row_mirror row_mask:0xf bank_mask:0xf bound_ctrl:1
	v_pk_fma_f32 v[12:13], v[4:5], v[172:173], v[12:13]
	v_pk_fma_f32 v[14:15], v[6:7], v[174:175], v[14:15]
	ds_read_b128 v[166:169], v0 offset:14080
	ds_read_b128 v[50:53], v18 offset:29712
	v_pk_fma_f32 v[4:5], v[184:185], v[20:21], v[12:13] op_sel_hi:[1,0,1]
	v_pk_fma_f32 v[6:7], v[186:187], v[20:21], v[14:15] op_sel_hi:[1,0,1]
	s_waitcnt lgkmcnt(6)
	v_pk_mul_f32 v[8:9], v[6:7], v[220:221]
	v_pk_fma_f32 v[8:9], v[4:5], v[218:219], v[8:9]
	v_pk_mul_f32 v[10:11], v[6:7], v[190:191]
	v_add_f32_e32 v20, v8, v9
	v_pk_fma_f32 v[10:11], v[4:5], v[188:189], v[10:11]
	v_pk_mul_f32 v[12:13], v[214:215], v[48:49] op_sel_hi:[1,0]
	v_add_f32_dpp v20, v20, v20 quad_perm:[1,0,3,2] row_mask:0xf bank_mask:0xf bound_ctrl:1
	v_add_f32_e32 v31, v10, v11
	v_pk_mul_f32 v[14:15], v[216:217], v[48:49] op_sel_hi:[1,0]
	v_add_f32_dpp v20, v20, v20 quad_perm:[2,3,0,1] row_mask:0xf bank_mask:0xf bound_ctrl:1
	ds_read_b128 v[172:175], v0 offset:14336
	ds_read_b128 v[176:179], v0 offset:14592
	v_add_f32_dpp v20, v20, v20 row_half_mirror row_mask:0xf bank_mask:0xf bound_ctrl:1
	ds_read_b128 v[180:183], v0 offset:14848
	ds_read_b128 v[184:187], v0 offset:15104
	v_add_f32_dpp v20, v20, v20 row_mirror row_mask:0xf bank_mask:0xf bound_ctrl:1
	v_pk_fma_f32 v[12:13], v[4:5], v[210:211], v[12:13]
	v_pk_fma_f32 v[14:15], v[6:7], v[212:213], v[14:15]
	ds_read_b128 v[188:191], v0 offset:15360
	v_pk_fma_f32 v[4:5], v[222:223], v[20:21], v[12:13] op_sel_hi:[1,0,1]
	v_pk_fma_f32 v[6:7], v[224:225], v[20:21], v[14:15] op_sel_hi:[1,0,1]
	s_waitcnt lgkmcnt(6)
	v_pk_mul_f32 v[8:9], v[6:7], v[160:161]
	v_pk_fma_f32 v[8:9], v[4:5], v[158:159], v[8:9]
	v_pk_mul_f32 v[10:11], v[6:7], v[228:229]
	v_add_f32_e32 v20, v8, v9
	v_pk_fma_f32 v[10:11], v[4:5], v[226:227], v[10:11]
	v_pk_mul_f32 v[12:13], v[154:155], v[48:49] op_sel:[0,1] op_sel_hi:[1,1]
	v_add_f32_dpp v20, v20, v20 quad_perm:[1,0,3,2] row_mask:0xf bank_mask:0xf bound_ctrl:1
	v_add_f32_e32 v32, v10, v11
	v_pk_mul_f32 v[14:15], v[156:157], v[48:49] op_sel:[0,1] op_sel_hi:[1,1]
	v_add_f32_dpp v20, v20, v20 quad_perm:[2,3,0,1] row_mask:0xf bank_mask:0xf bound_ctrl:1
	ds_read_b128 v[210:213], v0 offset:15616
	ds_read_b128 v[214:217], v0 offset:15872
	v_add_f32_dpp v20, v20, v20 row_half_mirror row_mask:0xf bank_mask:0xf bound_ctrl:1
	ds_read_b128 v[218:221], v0 offset:16128
	ds_read_b128 v[222:225], v0 offset:16384
	v_add_f32_dpp v20, v20, v20 row_mirror row_mask:0xf bank_mask:0xf bound_ctrl:1
	v_pk_fma_f32 v[12:13], v[4:5], v[150:151], v[12:13]
	v_pk_fma_f32 v[14:15], v[6:7], v[152:153], v[14:15]
	ds_read_b128 v[226:229], v0 offset:16640
	v_pk_fma_f32 v[4:5], v[162:163], v[20:21], v[12:13] op_sel_hi:[1,0,1]
	v_pk_fma_f32 v[6:7], v[164:165], v[20:21], v[14:15] op_sel_hi:[1,0,1]
	s_waitcnt lgkmcnt(5)
	v_pk_mul_f32 v[8:9], v[6:7], v[182:183]
	v_pk_fma_f32 v[8:9], v[4:5], v[180:181], v[8:9]
	v_pk_mul_f32 v[10:11], v[6:7], v[168:169]
	v_add_f32_e32 v20, v8, v9
	v_pk_fma_f32 v[10:11], v[4:5], v[166:167], v[10:11]
	v_pk_mul_f32 v[12:13], v[176:177], v[50:51] op_sel_hi:[1,0]
	v_add_f32_dpp v20, v20, v20 quad_perm:[1,0,3,2] row_mask:0xf bank_mask:0xf bound_ctrl:1
	v_add_f32_e32 v33, v10, v11
	v_pk_mul_f32 v[14:15], v[178:179], v[50:51] op_sel_hi:[1,0]
	v_add_f32_dpp v20, v20, v20 quad_perm:[2,3,0,1] row_mask:0xf bank_mask:0xf bound_ctrl:1
	ds_read_b128 v[150:153], v0 offset:16896
	ds_read_b128 v[154:157], v0 offset:17152
	v_add_f32_dpp v20, v20, v20 row_half_mirror row_mask:0xf bank_mask:0xf bound_ctrl:1
	ds_read_b128 v[158:161], v0 offset:17408
	ds_read_b128 v[162:165], v0 offset:17664
	v_add_f32_dpp v20, v20, v20 row_mirror row_mask:0xf bank_mask:0xf bound_ctrl:1
	v_pk_fma_f32 v[12:13], v[4:5], v[172:173], v[12:13]
	v_pk_fma_f32 v[14:15], v[6:7], v[174:175], v[14:15]
	ds_read_b128 v[166:169], v0 offset:17920
	v_pk_fma_f32 v[4:5], v[184:185], v[20:21], v[12:13] op_sel_hi:[1,0,1]
	v_pk_fma_f32 v[6:7], v[186:187], v[20:21], v[14:15] op_sel_hi:[1,0,1]
	s_waitcnt lgkmcnt(5)
	v_pk_mul_f32 v[8:9], v[6:7], v[220:221]
	v_pk_fma_f32 v[8:9], v[4:5], v[218:219], v[8:9]
	v_pk_mul_f32 v[10:11], v[6:7], v[190:191]
	v_add_f32_e32 v20, v8, v9
	v_pk_fma_f32 v[10:11], v[4:5], v[188:189], v[10:11]
	v_pk_mul_f32 v[12:13], v[214:215], v[50:51] op_sel:[0,1] op_sel_hi:[1,1]
	v_add_f32_dpp v20, v20, v20 quad_perm:[1,0,3,2] row_mask:0xf bank_mask:0xf bound_ctrl:1
	v_add_f32_e32 v34, v10, v11
	v_pk_mul_f32 v[14:15], v[216:217], v[50:51] op_sel:[0,1] op_sel_hi:[1,1]
	v_add_f32_dpp v20, v20, v20 quad_perm:[2,3,0,1] row_mask:0xf bank_mask:0xf bound_ctrl:1
	ds_read_b128 v[172:175], v0 offset:18176
	ds_read_b128 v[176:179], v0 offset:18432
	v_add_f32_dpp v20, v20, v20 row_half_mirror row_mask:0xf bank_mask:0xf bound_ctrl:1
	ds_read_b128 v[180:183], v0 offset:18688
	ds_read_b128 v[184:187], v0 offset:18944
	v_add_f32_dpp v20, v20, v20 row_mirror row_mask:0xf bank_mask:0xf bound_ctrl:1
	v_pk_fma_f32 v[12:13], v[4:5], v[210:211], v[12:13]
	v_pk_fma_f32 v[14:15], v[6:7], v[212:213], v[14:15]
	ds_read_b128 v[188:191], v0 offset:19200
	ds_read_b128 v[46:49], v18 offset:29728
	v_pk_fma_f32 v[4:5], v[222:223], v[20:21], v[12:13] op_sel_hi:[1,0,1]
	v_pk_fma_f32 v[6:7], v[224:225], v[20:21], v[14:15] op_sel_hi:[1,0,1]
	s_waitcnt lgkmcnt(6)
	v_pk_mul_f32 v[8:9], v[6:7], v[160:161]
	v_pk_fma_f32 v[8:9], v[4:5], v[158:159], v[8:9]
	v_pk_mul_f32 v[10:11], v[6:7], v[228:229]
	v_add_f32_e32 v20, v8, v9
	v_pk_fma_f32 v[10:11], v[4:5], v[226:227], v[10:11]
	v_pk_mul_f32 v[12:13], v[154:155], v[52:53] op_sel_hi:[1,0]
	v_add_f32_dpp v20, v20, v20 quad_perm:[1,0,3,2] row_mask:0xf bank_mask:0xf bound_ctrl:1
	v_add_f32_e32 v35, v10, v11
	v_pk_mul_f32 v[14:15], v[156:157], v[52:53] op_sel_hi:[1,0]
	v_add_f32_dpp v20, v20, v20 quad_perm:[2,3,0,1] row_mask:0xf bank_mask:0xf bound_ctrl:1
	ds_read_b128 v[210:213], v0 offset:19456
	ds_read_b128 v[214:217], v0 offset:19712
	v_add_f32_dpp v20, v20, v20 row_half_mirror row_mask:0xf bank_mask:0xf bound_ctrl:1
	ds_read_b128 v[218:221], v0 offset:19968
	ds_read_b128 v[222:225], v0 offset:20224
	v_add_f32_dpp v20, v20, v20 row_mirror row_mask:0xf bank_mask:0xf bound_ctrl:1
	v_pk_fma_f32 v[12:13], v[4:5], v[150:151], v[12:13]
	v_pk_fma_f32 v[14:15], v[6:7], v[152:153], v[14:15]
	ds_read_b128 v[226:229], v0 offset:20480
	v_pk_fma_f32 v[4:5], v[162:163], v[20:21], v[12:13] op_sel_hi:[1,0,1]
	v_pk_fma_f32 v[6:7], v[164:165], v[20:21], v[14:15] op_sel_hi:[1,0,1]
	s_waitcnt lgkmcnt(6)
	v_pk_mul_f32 v[8:9], v[6:7], v[182:183]
	v_pk_fma_f32 v[8:9], v[4:5], v[180:181], v[8:9]
	v_pk_mul_f32 v[10:11], v[6:7], v[168:169]
	v_add_f32_e32 v20, v8, v9
	v_pk_fma_f32 v[10:11], v[4:5], v[166:167], v[10:11]
	v_pk_mul_f32 v[12:13], v[176:177], v[52:53] op_sel:[0,1] op_sel_hi:[1,1]
	v_add_f32_dpp v20, v20, v20 quad_perm:[1,0,3,2] row_mask:0xf bank_mask:0xf bound_ctrl:1
	v_add_f32_e32 v36, v10, v11
	v_pk_mul_f32 v[14:15], v[178:179], v[52:53] op_sel:[0,1] op_sel_hi:[1,1]
	v_add_f32_dpp v20, v20, v20 quad_perm:[2,3,0,1] row_mask:0xf bank_mask:0xf bound_ctrl:1
	ds_read_b128 v[150:153], v0 offset:20736
	ds_read_b128 v[154:157], v0 offset:20992
	v_add_f32_dpp v20, v20, v20 row_half_mirror row_mask:0xf bank_mask:0xf bound_ctrl:1
	ds_read_b128 v[158:161], v0 offset:21248
	ds_read_b128 v[162:165], v0 offset:21504
	v_add_f32_dpp v20, v20, v20 row_mirror row_mask:0xf bank_mask:0xf bound_ctrl:1
	v_pk_fma_f32 v[12:13], v[4:5], v[172:173], v[12:13]
	v_pk_fma_f32 v[14:15], v[6:7], v[174:175], v[14:15]
	ds_read_b128 v[166:169], v0 offset:21760
	v_pk_fma_f32 v[4:5], v[184:185], v[20:21], v[12:13] op_sel_hi:[1,0,1]
	v_pk_fma_f32 v[6:7], v[186:187], v[20:21], v[14:15] op_sel_hi:[1,0,1]
	s_waitcnt lgkmcnt(5)
	v_pk_mul_f32 v[8:9], v[6:7], v[220:221]
	v_pk_fma_f32 v[8:9], v[4:5], v[218:219], v[8:9]
	v_pk_mul_f32 v[10:11], v[6:7], v[190:191]
	v_add_f32_e32 v20, v8, v9
	v_pk_fma_f32 v[10:11], v[4:5], v[188:189], v[10:11]
	v_pk_mul_f32 v[12:13], v[214:215], v[46:47] op_sel_hi:[1,0]
	v_add_f32_dpp v20, v20, v20 quad_perm:[1,0,3,2] row_mask:0xf bank_mask:0xf bound_ctrl:1
	v_add_f32_e32 v37, v10, v11
	v_pk_mul_f32 v[14:15], v[216:217], v[46:47] op_sel_hi:[1,0]
	v_add_f32_dpp v20, v20, v20 quad_perm:[2,3,0,1] row_mask:0xf bank_mask:0xf bound_ctrl:1
	ds_read_b128 v[172:175], v0 offset:22016
	ds_read_b128 v[176:179], v0 offset:22272
	v_add_f32_dpp v20, v20, v20 row_half_mirror row_mask:0xf bank_mask:0xf bound_ctrl:1
	ds_read_b128 v[180:183], v0 offset:22528
	ds_read_b128 v[184:187], v0 offset:22784
	v_add_f32_dpp v20, v20, v20 row_mirror row_mask:0xf bank_mask:0xf bound_ctrl:1
	v_pk_fma_f32 v[12:13], v[4:5], v[210:211], v[12:13]
	v_pk_fma_f32 v[14:15], v[6:7], v[212:213], v[14:15]
	ds_read_b128 v[188:191], v0 offset:23040
	v_pk_fma_f32 v[4:5], v[222:223], v[20:21], v[12:13] op_sel_hi:[1,0,1]
	v_pk_fma_f32 v[6:7], v[224:225], v[20:21], v[14:15] op_sel_hi:[1,0,1]
	s_waitcnt lgkmcnt(5)
	v_pk_mul_f32 v[8:9], v[6:7], v[160:161]
	v_pk_fma_f32 v[8:9], v[4:5], v[158:159], v[8:9]
	v_pk_mul_f32 v[10:11], v[6:7], v[228:229]
	v_add_f32_e32 v20, v8, v9
	v_pk_fma_f32 v[10:11], v[4:5], v[226:227], v[10:11]
	v_pk_mul_f32 v[12:13], v[154:155], v[46:47] op_sel:[0,1] op_sel_hi:[1,1]
	v_add_f32_dpp v20, v20, v20 quad_perm:[1,0,3,2] row_mask:0xf bank_mask:0xf bound_ctrl:1
	v_add_f32_e32 v38, v10, v11
	v_pk_mul_f32 v[14:15], v[156:157], v[46:47] op_sel:[0,1] op_sel_hi:[1,1]
	v_add_f32_dpp v20, v20, v20 quad_perm:[2,3,0,1] row_mask:0xf bank_mask:0xf bound_ctrl:1
	ds_read_b128 v[210:213], v0 offset:23296
	ds_read_b128 v[214:217], v0 offset:23552
	v_add_f32_dpp v20, v20, v20 row_half_mirror row_mask:0xf bank_mask:0xf bound_ctrl:1
	ds_read_b128 v[218:221], v0 offset:23808
	ds_read_b128 v[222:225], v0 offset:24064
	v_add_f32_dpp v20, v20, v20 row_mirror row_mask:0xf bank_mask:0xf bound_ctrl:1
	v_pk_fma_f32 v[12:13], v[4:5], v[150:151], v[12:13]
	v_pk_fma_f32 v[14:15], v[6:7], v[152:153], v[14:15]
	ds_read_b128 v[226:229], v0 offset:24320
	ds_read_b128 v[50:53], v18 offset:29744
	v_pk_fma_f32 v[4:5], v[162:163], v[20:21], v[12:13] op_sel_hi:[1,0,1]
	v_pk_fma_f32 v[6:7], v[164:165], v[20:21], v[14:15] op_sel_hi:[1,0,1]
	s_waitcnt lgkmcnt(6)
	v_pk_mul_f32 v[8:9], v[6:7], v[182:183]
	v_pk_fma_f32 v[8:9], v[4:5], v[180:181], v[8:9]
	v_pk_mul_f32 v[10:11], v[6:7], v[168:169]
	v_add_f32_e32 v20, v8, v9
	v_pk_fma_f32 v[10:11], v[4:5], v[166:167], v[10:11]
	v_pk_mul_f32 v[12:13], v[176:177], v[48:49] op_sel_hi:[1,0]
	v_add_f32_dpp v20, v20, v20 quad_perm:[1,0,3,2] row_mask:0xf bank_mask:0xf bound_ctrl:1
	v_add_f32_e32 v39, v10, v11
	v_pk_mul_f32 v[14:15], v[178:179], v[48:49] op_sel_hi:[1,0]
	v_add_f32_dpp v20, v20, v20 quad_perm:[2,3,0,1] row_mask:0xf bank_mask:0xf bound_ctrl:1
	ds_read_b128 v[150:153], v0 offset:24576
	ds_read_b128 v[154:157], v0 offset:24832
	v_add_f32_dpp v20, v20, v20 row_half_mirror row_mask:0xf bank_mask:0xf bound_ctrl:1
	ds_read_b128 v[158:161], v0 offset:25088
	ds_read_b128 v[162:165], v0 offset:25344
	v_add_f32_dpp v20, v20, v20 row_mirror row_mask:0xf bank_mask:0xf bound_ctrl:1
	v_pk_fma_f32 v[12:13], v[4:5], v[172:173], v[12:13]
	v_pk_fma_f32 v[14:15], v[6:7], v[174:175], v[14:15]
	ds_read_b128 v[166:169], v0 offset:25600
	v_pk_fma_f32 v[4:5], v[184:185], v[20:21], v[12:13] op_sel_hi:[1,0,1]
	v_pk_fma_f32 v[6:7], v[186:187], v[20:21], v[14:15] op_sel_hi:[1,0,1]
	s_waitcnt lgkmcnt(6)
	v_pk_mul_f32 v[8:9], v[6:7], v[220:221]
	v_pk_fma_f32 v[8:9], v[4:5], v[218:219], v[8:9]
	v_pk_mul_f32 v[10:11], v[6:7], v[190:191]
	v_add_f32_e32 v20, v8, v9
	v_pk_fma_f32 v[10:11], v[4:5], v[188:189], v[10:11]
	v_pk_mul_f32 v[12:13], v[214:215], v[48:49] op_sel:[0,1] op_sel_hi:[1,1]
	v_add_f32_dpp v20, v20, v20 quad_perm:[1,0,3,2] row_mask:0xf bank_mask:0xf bound_ctrl:1
	v_add_f32_e32 v40, v10, v11
	v_pk_mul_f32 v[14:15], v[216:217], v[48:49] op_sel:[0,1] op_sel_hi:[1,1]
	v_add_f32_dpp v20, v20, v20 quad_perm:[2,3,0,1] row_mask:0xf bank_mask:0xf bound_ctrl:1
	ds_read_b128 v[172:175], v0 offset:25856
	ds_read_b128 v[176:179], v0 offset:26112
	v_add_f32_dpp v20, v20, v20 row_half_mirror row_mask:0xf bank_mask:0xf bound_ctrl:1
	ds_read_b128 v[180:183], v0 offset:26368
	ds_read_b128 v[184:187], v0 offset:26624
	v_add_f32_dpp v20, v20, v20 row_mirror row_mask:0xf bank_mask:0xf bound_ctrl:1
	v_pk_fma_f32 v[12:13], v[4:5], v[210:211], v[12:13]
	v_pk_fma_f32 v[14:15], v[6:7], v[212:213], v[14:15]
	ds_read_b128 v[188:191], v0 offset:26880
	v_pk_fma_f32 v[4:5], v[222:223], v[20:21], v[12:13] op_sel_hi:[1,0,1]
	v_pk_fma_f32 v[6:7], v[224:225], v[20:21], v[14:15] op_sel_hi:[1,0,1]
	s_waitcnt lgkmcnt(5)
	v_pk_mul_f32 v[8:9], v[6:7], v[160:161]
	v_pk_fma_f32 v[8:9], v[4:5], v[158:159], v[8:9]
	v_pk_mul_f32 v[10:11], v[6:7], v[228:229]
	v_add_f32_e32 v20, v8, v9
	v_pk_fma_f32 v[10:11], v[4:5], v[226:227], v[10:11]
	v_pk_mul_f32 v[12:13], v[154:155], v[50:51] op_sel_hi:[1,0]
	v_add_f32_dpp v20, v20, v20 quad_perm:[1,0,3,2] row_mask:0xf bank_mask:0xf bound_ctrl:1
	v_add_f32_e32 v41, v10, v11
	v_pk_mul_f32 v[14:15], v[156:157], v[50:51] op_sel_hi:[1,0]
	v_add_f32_dpp v20, v20, v20 quad_perm:[2,3,0,1] row_mask:0xf bank_mask:0xf bound_ctrl:1
	ds_read_b128 v[210:213], v0 offset:27136
	ds_read_b128 v[214:217], v0 offset:27392
	v_add_f32_dpp v20, v20, v20 row_half_mirror row_mask:0xf bank_mask:0xf bound_ctrl:1
	ds_read_b128 v[218:221], v0 offset:27648
	ds_read_b128 v[222:225], v0 offset:27904
	v_add_f32_dpp v20, v20, v20 row_mirror row_mask:0xf bank_mask:0xf bound_ctrl:1
	v_pk_fma_f32 v[12:13], v[4:5], v[150:151], v[12:13]
	v_pk_fma_f32 v[14:15], v[6:7], v[152:153], v[14:15]
	ds_read_b128 v[226:229], v0 offset:28160
	v_pk_fma_f32 v[4:5], v[162:163], v[20:21], v[12:13] op_sel_hi:[1,0,1]
	v_pk_fma_f32 v[6:7], v[164:165], v[20:21], v[14:15] op_sel_hi:[1,0,1]
	s_waitcnt lgkmcnt(5)
	v_pk_mul_f32 v[8:9], v[6:7], v[182:183]
	v_pk_fma_f32 v[8:9], v[4:5], v[180:181], v[8:9]
	v_pk_mul_f32 v[10:11], v[6:7], v[168:169]
	v_add_f32_e32 v20, v8, v9
	v_pk_fma_f32 v[10:11], v[4:5], v[166:167], v[10:11]
	v_pk_mul_f32 v[12:13], v[176:177], v[50:51] op_sel:[0,1] op_sel_hi:[1,1]
	v_add_f32_dpp v20, v20, v20 quad_perm:[1,0,3,2] row_mask:0xf bank_mask:0xf bound_ctrl:1
	v_add_f32_e32 v42, v10, v11
	v_pk_mul_f32 v[14:15], v[178:179], v[50:51] op_sel:[0,1] op_sel_hi:[1,1]
	v_add_f32_dpp v20, v20, v20 quad_perm:[2,3,0,1] row_mask:0xf bank_mask:0xf bound_ctrl:1
	ds_read_b128 v[150:153], v0 offset:28416
	ds_read_b128 v[154:157], v0 offset:28672
	v_add_f32_dpp v20, v20, v20 row_half_mirror row_mask:0xf bank_mask:0xf bound_ctrl:1
	ds_read_b128 v[158:161], v0 offset:28928
	ds_read_b128 v[162:165], v0 offset:29184
	v_add_f32_dpp v20, v20, v20 row_mirror row_mask:0xf bank_mask:0xf bound_ctrl:1
	v_pk_fma_f32 v[12:13], v[4:5], v[172:173], v[12:13]
	v_pk_fma_f32 v[14:15], v[6:7], v[174:175], v[14:15]
	ds_read_b128 v[166:169], v0 offset:29440
	v_pk_fma_f32 v[4:5], v[184:185], v[20:21], v[12:13] op_sel_hi:[1,0,1]
	v_pk_fma_f32 v[6:7], v[186:187], v[20:21], v[14:15] op_sel_hi:[1,0,1]
	ds_read_b32 v3, v22
	s_waitcnt lgkmcnt(6)
	v_pk_mul_f32 v[8:9], v[6:7], v[220:221]
	v_pk_fma_f32 v[8:9], v[4:5], v[218:219], v[8:9]
	v_pk_mul_f32 v[10:11], v[6:7], v[190:191]
	v_add_f32_e32 v20, v8, v9
	v_pk_fma_f32 v[10:11], v[4:5], v[188:189], v[10:11]
	v_pk_mul_f32 v[12:13], v[214:215], v[52:53] op_sel_hi:[1,0]
	v_add_f32_dpp v20, v20, v20 quad_perm:[1,0,3,2] row_mask:0xf bank_mask:0xf bound_ctrl:1
	v_add_f32_e32 v43, v10, v11
	v_pk_mul_f32 v[14:15], v[216:217], v[52:53] op_sel_hi:[1,0]
	v_add_f32_dpp v20, v20, v20 quad_perm:[2,3,0,1] row_mask:0xf bank_mask:0xf bound_ctrl:1
	v_pk_fma_f32 v[12:13], v[4:5], v[210:211], v[12:13]
	v_pk_fma_f32 v[14:15], v[6:7], v[212:213], v[14:15]
	v_add_f32_dpp v20, v20, v20 row_half_mirror row_mask:0xf bank_mask:0xf bound_ctrl:1
	s_nop 1
	v_add_f32_dpp v20, v20, v20 row_mirror row_mask:0xf bank_mask:0xf bound_ctrl:1
	v_pk_fma_f32 v[4:5], v[222:223], v[20:21], v[12:13] op_sel_hi:[1,0,1]
	v_pk_fma_f32 v[6:7], v[224:225], v[20:21], v[14:15] op_sel_hi:[1,0,1]
	s_waitcnt lgkmcnt(1)
	v_pk_mul_f32 v[8:9], v[6:7], v[160:161]
	v_pk_fma_f32 v[8:9], v[4:5], v[158:159], v[8:9]
	v_pk_mul_f32 v[10:11], v[6:7], v[228:229]
	v_add_f32_e32 v20, v8, v9
	v_pk_fma_f32 v[10:11], v[4:5], v[226:227], v[10:11]
	v_pk_mul_f32 v[12:13], v[154:155], v[52:53] op_sel:[0,1] op_sel_hi:[1,1]
	v_add_f32_dpp v20, v20, v20 quad_perm:[1,0,3,2] row_mask:0xf bank_mask:0xf bound_ctrl:1
	v_add_f32_e32 v44, v10, v11
	v_pk_mul_f32 v[14:15], v[156:157], v[52:53] op_sel:[0,1] op_sel_hi:[1,1]
	v_add_f32_dpp v20, v20, v20 quad_perm:[2,3,0,1] row_mask:0xf bank_mask:0xf bound_ctrl:1
	v_pk_fma_f32 v[12:13], v[4:5], v[150:151], v[12:13]
	v_pk_fma_f32 v[14:15], v[6:7], v[152:153], v[14:15]
	v_add_f32_dpp v20, v20, v20 row_half_mirror row_mask:0xf bank_mask:0xf bound_ctrl:1
	s_nop 1
	v_add_f32_dpp v20, v20, v20 row_mirror row_mask:0xf bank_mask:0xf bound_ctrl:1
	v_pk_fma_f32 v[4:5], v[162:163], v[20:21], v[12:13] op_sel_hi:[1,0,1]
	v_pk_fma_f32 v[6:7], v[164:165], v[20:21], v[14:15] op_sel_hi:[1,0,1]
	v_pk_mul_f32 v[10:11], v[6:7], v[168:169]
	v_pk_fma_f32 v[10:11], v[4:5], v[166:167], v[10:11]
	v_add_u32_e32 v2, v1, v232
	v_add_f32_e32 v45, v10, v11
	s_add_i32 s72, s72, 1
	s_cmpk_eq_i32 s72, 0x200
	s_cbranch_scc1 .Lc3_last
	s_waitcnt lgkmcnt(0)
	v_cmp_gt_i32_e32 vcc, v3, v23
	ds_write_b128 v2, v[30:33] offset:9216
	ds_write_b128 v2, v[34:37] offset:10336
	ds_write_b128 v2, v[38:41] offset:11456
	ds_write_b128 v2, v[42:45] offset:12576
	v_add_u32_e32 v24, 1, v24
	ds_write_b32 v19, v24 offset:16
	v_mov_b32_e32 v19, v22
	v_mov_b32_e32 v24, v23
	s_cbranch_vccz .Lc3_entry
	s_mul_i32 s0, s73, 0x5100
	v_add_u32_e32 v1, s0, v87
	v_lshl_add_u32 v0, v125, 2, v1
	v_lshl_add_u32 v18, v78, 6, v1
	ds_read_b128 v[150:153], v0 offset:9216
	ds_read_b128 v[154:157], v0 offset:9472
	ds_read_b128 v[158:161], v0 offset:9728
	ds_read_b128 v[162:165], v0 offset:9984
	ds_read_b128 v[166:169], v0 offset:10240
	ds_read_b128 v[46:49], v18 offset:29696
	ds_read_b128 v[172:175], v0 offset:10496
	ds_read_b128 v[176:179], v0 offset:10752
	ds_read_b128 v[180:183], v0 offset:11008
	ds_read_b128 v[184:187], v0 offset:11264
	ds_read_b128 v[188:191], v0 offset:11520
	s_add_i32 s73, s73, 1
	s_cmp_eq_u32 s73, 3
	s_cselect_b32 s73, 0, s73
	s_addc_u32 s1, s1, 0
	v_lshl_add_u32 v22, s73, 2, v123
	v_add_u32_e32 v23, s1, v130
	s_branch .Lc3_steps

.Lp4_a_noys:
	s_add_i32 s1, s78, 2
	s_and_b32 s0, s1, 0xffff
	s_mul_i32 s0, s0, 0xaaab
	s_lshr_b32 s0, s0, 17
	s_mul_i32 s0, s0, 3
	s_sub_i32 s0, s1, s0
	v_lshl_add_u32 v131, s0, 2, v123
	s_cmpk_ge_i32 s78, 0x200
	s_cbranch_scc1 .Lp4_a_fl
	v_and_b32_e32 v131, 3, v122
	v_lshrrev_b32_e32 v132, 2, v122
	v_lshl_or_b32 v131, v131, 4, v132
	v_lshl_add_u32 v105, v131, 2, v105
	ds_write_b32 v105, v99 offset:29696
	v_add_u32_e32 v103, 1, v103
	ds_write_b32 v101, v103

.Lp4_b_noys:
	s_add_i32 s1, s78, 2
	s_and_b32 s0, s1, 0xffff
	s_mul_i32 s0, s0, 0xaaab
	s_lshr_b32 s0, s0, 17
	s_mul_i32 s0, s0, 3
	s_sub_i32 s0, s1, s0
	v_lshl_add_u32 v131, s0, 2, v123
	s_cmpk_ge_i32 s78, 0x200
	s_cbranch_scc1 .Lp4_b_fl
	v_and_b32_e32 v131, 3, v122
	v_lshrrev_b32_e32 v132, 2, v122
	v_lshl_or_b32 v131, v131, 4, v132
	v_lshl_add_u32 v105, v131, 2, v105
	ds_write_b32 v105, v242 offset:29696
	v_add_u32_e32 v103, 1, v103
	ds_write_b32 v101, v103
